# attnC softmax: packed fp32 ops (v_pk_add_f32) split into single-lane ops
# baseline (speedup 1.0000x reference)
; #define LAS __attribute__((address_space(3)))
; __device__ __forceinline__ float fexp2(float x) { return __builtin_amdgcn_exp2f(x); }
; template <bool KLDS>
; __device__ __forceinline__ void attn_step(const bf16x8 (&kf)[4], LAS const unsigned char* kb, const bf16x8 (&vf)[2][2], const bf16x8 (&qf)[4], f32x16& o0, f32x16& o1, float& m, float& l, int lane, int maskmode) {
;     ...
;     for (int s = 0; s < 4; ++s) {
;         if (KLDS) { const int pc = (2 * s + h) ^ ((ql >> 1) & 7); const bf16x8 k1 = *(const LAS bf16x8*)(kb + ql * 128 + pc * 16); S = __builtin_amdgcn_mfma_f32_32x32x16_bf16(k1, qf[s], S, 0, 0, 0); }
;         else S = __builtin_amdgcn_mfma_f32_32x32x16_bf16(kf[s], qf[s], S, 0, 0, 0);
;     }
;     if (maskmode) {
; #pragma unroll
;         for (int i = 0; i < 16; ++i) { const int kr = (i & 3) + 8 * (i >> 2) + 4 * h; const bool ok = (maskmode == 1) ? (kr >= ql) : (kr <= ql); S[i] = ok ? S[i] : -1e30f; }
;     }
;     float tm = S[0];
; #pragma unroll
;     for (int i = 1; i < 16; ++i) tm = fmaxf(tm, S[i]);
;     tm = fmaxf(tm, __shfl_xor(tm, 32));
;     const float mn = fmaxf(m, tm), al = fexp2(m - mn); m = mn;
;     float ps = 0.f;
; #pragma unroll
;     for (int i = 0; i < 16; ++i) { S[i] = fexp2(S[i] - mn); ps += S[i]; }
;     l = l * al + ps;
; #pragma unroll
;     for (int i = 0; i < 16; ++i) { o0[i] *= al; o1[i] *= al; }
; __device__ __forceinline__ void attnC_unit(const Args& a, int unit, LAS unsigned char* lds) {
;     ...
;         LAS unsigned char* cur = lds + (kt & 1) * 16384;
;         LAS unsigned char* nxt = lds + ((kt + 1) & 1) * 16384;
;         if (kt + 1 < 32) { *(LAS u32x4*)(nxt + kwo) = rk; *(LAS u32x4*)(nxt + vwo) = rv; }
;         if (kt + 2 < 32) { rk = *(const u32x4*)(kg + (size_t)(kt + 2) * TSTEP); rv = *(const u32x4*)(vg + (size_t)(kt + 2) * TSTEP); }
; #pragma unroll
;         for (int j = 0; j < 2; ++j) {
;             bf16x8 kf[4], vf[2][2];
;             load_kf(cur + j * 4096, kf, lane); load_vf(cur + 8192 + j * 4096, vf, lane);
; #pragma unroll
;             for (int e = 0; e < 2; ++e) attn_step<false>(kf, cur, vf, qf[e], o0[e], o1[e], m[e], l[e], lane, 0);
.LBB0_254:
	v_readfirstlane_b32 s5, v225
	s_add_i32 s4, s2, 0xffffc000
	s_and_b32 s4, s4, 0x4000
	v_add_u32_e32 v64, s4, v252
	v_add_u32_e32 v124, v64, v231
	v_add_u32_e32 v123, v64, v239
	v_add_u32_e32 v121, v64, v232
	v_add_u32_e32 v120, v64, v241
	v_add3_u32 v122, s4, v157, v156
	s_addk_i32 s2, 0x4000
	s_add_i32 s3, s3, 1
	v_lshl_add_u64 v[180:181], v[180:181], 0, s[18:19]
	s_mov_b32 s9, 0x41000000
	ds_read_b128 v[126:129], v124
	ds_read_b128 v[130:133], v123
	ds_read_b128 v[138:141], v121
	ds_read_b128 v[142:145], v120
	ds_read_b64_tr_b16 v[146:147], v122 offset:8192
	ds_read_b64_tr_b16 v[148:149], v122 offset:9216
	ds_read_b64_tr_b16 v[204:205], v122 offset:8256
	ds_read_b64_tr_b16 v[206:207], v122 offset:9280
	ds_read_b64_tr_b16 v[208:209], v122 offset:10240
	ds_read_b64_tr_b16 v[210:211], v122 offset:11264
	ds_read_b64_tr_b16 v[212:213], v122 offset:10304
	ds_read_b64_tr_b16 v[214:215], v122 offset:11328
	s_waitcnt lgkmcnt(11)
	v_mfma_f32_32x32x16_bf16 v[64:79], v[126:129], v[80:83], 0
	v_mfma_f32_32x32x16_bf16 v[158:173], v[126:129], v[96:99], 0
	s_waitcnt lgkmcnt(10)
	v_mfma_f32_32x32x16_bf16 v[64:79], v[130:133], v[84:87], v[64:79]
	v_mfma_f32_32x32x16_bf16 v[158:173], v[130:133], v[100:103], v[158:173]
	s_waitcnt lgkmcnt(9)
	v_mfma_f32_32x32x16_bf16 v[64:79], v[138:141], v[88:91], v[64:79]
	v_mfma_f32_32x32x16_bf16 v[158:173], v[138:141], v[104:107], v[158:173]
	s_waitcnt lgkmcnt(8)
	v_mfma_f32_32x32x16_bf16 v[64:79], v[142:145], v[92:95], v[64:79]
	v_mfma_f32_32x32x16_bf16 v[158:173], v[142:145], v[108:111], v[158:173]
	s_nop 10
	v_max3_f32 v152, v64, v65, v66
	v_max3_f32 v150, v158, v159, v160
	v_max3_f32 v152, v152, v67, v68
	v_max3_f32 v150, v150, v161, v162
	v_max3_f32 v152, v152, v69, v70
	v_max3_f32 v150, v150, v163, v164
	v_max3_f32 v152, v152, v71, v72
	v_max3_f32 v150, v150, v165, v166
	v_max3_f32 v152, v152, v73, v74
	v_max3_f32 v150, v150, v167, v168
	v_max3_f32 v152, v152, v75, v76
	v_max3_f32 v150, v150, v169, v170
	v_max3_f32 v152, v152, v77, v78
	v_max3_f32 v150, v150, v171, v172
	v_max_f32_e32 v152, v152, v79
	v_max_f32_e32 v150, v150, v173
	v_mov_b32_e32 v153, v152
	v_mov_b32_e32 v151, v150
	s_nop 1
	s_nop 1
	v_permlane32_swap_b32_e32 v153, v152
	v_permlane32_swap_b32_e32 v151, v150
	v_max_f32_e32 v152, v152, v153
	v_max_f32_e32 v150, v150, v151
	v_sub_f32_e32 v153, v152, v235
	v_sub_f32_e32 v151, v150, v136
	v_cmp_lt_f32_e64 s[10:11], s9, v153
	v_cmp_lt_f32_e64 s[4:5], s9, v151
	s_nop 0
	s_nop 0
	v_cndmask_b32_e64 v202, v235, v152, s[10:11]
	v_cndmask_b32_e64 v200, v136, v150, s[4:5]
	v_sub_f32_e32 v154, v235, v202
	v_sub_f32_e32 v174, v136, v200
	v_exp_f32_e32 v154, v154
	v_exp_f32_e32 v174, v174
	v_sub_f32_e32 v64, v64, v202
	v_sub_f32_e32 v158, v158, v200
	v_sub_f32_e32 v65, v65, v202
	v_sub_f32_e32 v159, v159, v200
	v_sub_f32_e32 v66, v66, v202
	v_sub_f32_e32 v160, v160, v200
	v_sub_f32_e32 v67, v67, v202
	v_sub_f32_e32 v161, v161, v200
	v_sub_f32_e32 v68, v68, v202
	v_sub_f32_e32 v162, v162, v200
	v_sub_f32_e32 v69, v69, v202
	v_sub_f32_e32 v163, v163, v200
	v_sub_f32_e32 v70, v70, v202
	v_sub_f32_e32 v164, v164, v200
	v_sub_f32_e32 v71, v71, v202
	v_sub_f32_e32 v165, v165, v200
	v_sub_f32_e32 v72, v72, v202
	v_sub_f32_e32 v166, v166, v200
	v_sub_f32_e32 v73, v73, v202
	v_sub_f32_e32 v167, v167, v200
	v_sub_f32_e32 v74, v74, v202
	v_sub_f32_e32 v168, v168, v200
	v_sub_f32_e32 v75, v75, v202
	v_sub_f32_e32 v169, v169, v200
	v_sub_f32_e32 v76, v76, v202
	v_sub_f32_e32 v170, v170, v200
	v_sub_f32_e32 v77, v77, v202
	v_sub_f32_e32 v171, v171, v200
	v_sub_f32_e32 v78, v78, v202
	v_sub_f32_e32 v172, v172, v200
	v_sub_f32_e32 v79, v79, v202
	v_sub_f32_e32 v173, v173, v200
	v_mov_b32_e32 v235, v202
	v_mov_b32_e32 v136, v200
	v_exp_f32_e32 v64, v64
	v_exp_f32_e32 v158, v158
	v_exp_f32_e32 v65, v65
	v_exp_f32_e32 v159, v159
	v_exp_f32_e32 v66, v66
	v_exp_f32_e32 v160, v160
	v_add_f32_e32 v182, v64, v65
	v_add_f32_e32 v190, v158, v159
	v_exp_f32_e32 v67, v67
	v_exp_f32_e32 v161, v161
	v_add_f32_e32 v183, v66, v67
	v_add_f32_e32 v191, v160, v161
	v_exp_f32_e32 v68, v68
	v_exp_f32_e32 v162, v162
	v_exp_f32_e32 v69, v69
	v_exp_f32_e32 v163, v163
	v_add_f32_e32 v183, v183, v68
	v_add_f32_e32 v191, v191, v162
	v_exp_f32_e32 v70, v70
	v_exp_f32_e32 v164, v164
	v_add_f32_e32 v182, v182, v69
	v_add_f32_e32 v190, v190, v163
	v_exp_f32_e32 v71, v71
	v_exp_f32_e32 v165, v165
	v_add_f32_e32 v183, v183, v70
	v_add_f32_e32 v191, v191, v164
	v_exp_f32_e32 v72, v72
	v_exp_f32_e32 v166, v166
	v_add_f32_e32 v182, v182, v71
	v_add_f32_e32 v190, v190, v165
	v_exp_f32_e32 v73, v73
	v_exp_f32_e32 v167, v167
	v_add_f32_e32 v183, v183, v72
	v_add_f32_e32 v191, v191, v166
	v_exp_f32_e32 v74, v74
	v_exp_f32_e32 v168, v168
	v_add_f32_e32 v182, v182, v73
	v_add_f32_e32 v190, v190, v167
	v_exp_f32_e32 v75, v75
	v_exp_f32_e32 v169, v169
	v_add_f32_e32 v183, v183, v74
	v_add_f32_e32 v191, v191, v168
	v_exp_f32_e32 v76, v76
	v_exp_f32_e32 v170, v170
	v_add_f32_e32 v182, v182, v75
	v_add_f32_e32 v190, v190, v169
	v_exp_f32_e32 v77, v77
	v_exp_f32_e32 v171, v171
	v_add_f32_e32 v183, v183, v76
	v_add_f32_e32 v191, v191, v170
	v_exp_f32_e32 v78, v78
	v_exp_f32_e32 v172, v172
	v_add_f32_e32 v182, v182, v77
	v_add_f32_e32 v190, v190, v171
	v_exp_f32_e32 v79, v79
	v_exp_f32_e32 v173, v173
	v_add_f32_e32 v183, v183, v78
	v_add_f32_e32 v191, v191, v172
	s_nop 0
	s_nop 0
	v_add_f32_e32 v183, v183, v79
	v_add_f32_e32 v191, v191, v173
	v_add_f32_e32 v182, v182, v183
	v_add_f32_e32 v190, v190, v191
	v_fma_f32 v179, v179, v154, v182
	v_fma_f32 v178, v178, v174, v190
	v_cmp_neq_f32_e32 vcc, 1.0, v154
	s_cbranch_vccz .LaC_nr00
	v_pk_mul_f32 v[48:49], v[48:49], v[154:155] op_sel_hi:[1,0]
	v_pk_mul_f32 v[50:51], v[50:51], v[154:155] op_sel_hi:[1,0]
	v_pk_mul_f32 v[52:53], v[52:53], v[154:155] op_sel_hi:[1,0]
	v_pk_mul_f32 v[54:55], v[54:55], v[154:155] op_sel_hi:[1,0]
	v_pk_mul_f32 v[56:57], v[56:57], v[154:155] op_sel_hi:[1,0]
	v_pk_mul_f32 v[58:59], v[58:59], v[154:155] op_sel_hi:[1,0]
	v_pk_mul_f32 v[60:61], v[60:61], v[154:155] op_sel_hi:[1,0]
	v_pk_mul_f32 v[62:63], v[62:63], v[154:155] op_sel_hi:[1,0]
	v_pk_mul_f32 v[32:33], v[32:33], v[154:155] op_sel_hi:[1,0]
	v_pk_mul_f32 v[34:35], v[34:35], v[154:155] op_sel_hi:[1,0]
	v_pk_mul_f32 v[36:37], v[36:37], v[154:155] op_sel_hi:[1,0]
	v_pk_mul_f32 v[38:39], v[38:39], v[154:155] op_sel_hi:[1,0]
	v_pk_mul_f32 v[40:41], v[40:41], v[154:155] op_sel_hi:[1,0]
	v_pk_mul_f32 v[42:43], v[42:43], v[154:155] op_sel_hi:[1,0]
	v_pk_mul_f32 v[44:45], v[44:45], v[154:155] op_sel_hi:[1,0]
	v_pk_mul_f32 v[46:47], v[46:47], v[154:155] op_sel_hi:[1,0]

; #define LAS __attribute__((address_space(3)))
; __device__ __forceinline__ unsigned pk2n(float lo, float hi) { const f32x2v v = {lo, hi}; const bf16v2 b = __builtin_convertvector(v, bf16v2); return __builtin_bit_cast(unsigned, b); }
; __device__ __forceinline__ float fexp2(float x) { return __builtin_amdgcn_exp2f(x); }
; template <bool KLDS>
; __device__ __forceinline__ void attn_step(const bf16x8 (&kf)[4], LAS const unsigned char* kb, const bf16x8 (&vf)[2][2], const bf16x8 (&qf)[4], f32x16& o0, f32x16& o1, float& m, float& l, int lane, int maskmode) {
;     ...
;     for (int s = 0; s < 4; ++s) {
;         if (KLDS) { const int pc = (2 * s + h) ^ ((ql >> 1) & 7); const bf16x8 k1 = *(const LAS bf16x8*)(kb + ql * 128 + pc * 16); S = __builtin_amdgcn_mfma_f32_32x32x16_bf16(k1, qf[s], S, 0, 0, 0); }
;         else S = __builtin_amdgcn_mfma_f32_32x32x16_bf16(kf[s], qf[s], S, 0, 0, 0);
;     }
;     if (maskmode) {
; #pragma unroll
;         for (int i = 0; i < 16; ++i) { const int kr = (i & 3) + 8 * (i >> 2) + 4 * h; const bool ok = (maskmode == 1) ? (kr >= ql) : (kr <= ql); S[i] = ok ? S[i] : -1e30f; }
;     }
;     float tm = S[0];
; #pragma unroll
;     for (int i = 1; i < 16; ++i) tm = fmaxf(tm, S[i]);
;     tm = fmaxf(tm, __shfl_xor(tm, 32));
;     const float mn = fmaxf(m, tm), al = fexp2(m - mn); m = mn;
;     float ps = 0.f;
; #pragma unroll
;     for (int i = 0; i < 16; ++i) { S[i] = fexp2(S[i] - mn); ps += S[i]; }
;     l = l * al + ps;
; #pragma unroll
;     for (int i = 0; i < 16; ++i) { o0[i] *= al; o1[i] *= al; }
;     bf16x8 pf[2];
; #pragma unroll
;     for (int s2 = 0; s2 < 2; ++s2) {
;         u32x4 w; w.x = pk2n(S[8 * s2 + 0], S[8 * s2 + 1]); w.y = pk2n(S[8 * s2 + 2], S[8 * s2 + 3]); w.z = pk2n(S[8 * s2 + 4], S[8 * s2 + 5]); w.w = pk2n(S[8 * s2 + 6], S[8 * s2 + 7]);
;         pf[s2] = __builtin_bit_cast(bf16x8, w);
;     }
; #pragma unroll
;     for (int s2 = 0; s2 < 2; ++s2) {
;         o0 = __builtin_amdgcn_mfma_f32_32x32x16_bf16(vf[s2][0], pf[s2], o0, 0, 0, 0);
;         o1 = __builtin_amdgcn_mfma_f32_32x32x16_bf16(vf[s2][1], pf[s2], o1, 0, 0, 0);
;     }
.LaC_nr01:
	v_cvt_pk_bf16_f32 v64, v64, v65
	v_cvt_pk_bf16_f32 v158, v158, v159
	v_cvt_pk_bf16_f32 v65, v66, v67
	v_cvt_pk_bf16_f32 v159, v160, v161
	v_cvt_pk_bf16_f32 v66, v68, v69
	v_cvt_pk_bf16_f32 v160, v162, v163
	v_cvt_pk_bf16_f32 v67, v70, v71
	v_cvt_pk_bf16_f32 v161, v164, v165
	v_cvt_pk_bf16_f32 v68, v72, v73
	v_cvt_pk_bf16_f32 v162, v166, v167
	v_cvt_pk_bf16_f32 v69, v74, v75
	v_cvt_pk_bf16_f32 v163, v168, v169
	v_cvt_pk_bf16_f32 v70, v76, v77
	v_cvt_pk_bf16_f32 v164, v170, v171
	v_cvt_pk_bf16_f32 v71, v78, v79
	v_cvt_pk_bf16_f32 v165, v172, v173
	s_waitcnt lgkmcnt(0)
	v_mfma_f32_32x32x16_bf16 v[48:63], v[146:149], v[64:67], v[48:63]
	v_mfma_f32_32x32x16_bf16 v[16:31], v[146:149], v[158:161], v[16:31]
	v_mfma_f32_32x32x16_bf16 v[32:47], v[204:207], v[64:67], v[32:47]
	v_mfma_f32_32x32x16_bf16 v[0:15], v[204:207], v[158:161], v[0:15]
	v_mfma_f32_32x32x16_bf16 v[48:63], v[208:211], v[68:71], v[48:63]
	v_mfma_f32_32x32x16_bf16 v[16:31], v[208:211], v[162:165], v[16:31]
	v_mfma_f32_32x32x16_bf16 v[32:47], v[212:215], v[68:71], v[32:47]
	v_mfma_f32_32x32x16_bf16 v[0:15], v[212:215], v[162:165], v[0:15]
	ds_read_b128 v[126:129], v124 offset:4096
	ds_read_b128 v[130:133], v123 offset:4096
	ds_read_b128 v[138:141], v121 offset:4096
	ds_read_b128 v[142:145], v120 offset:4096
	ds_read_b64_tr_b16 v[146:147], v122 offset:12288
	ds_read_b64_tr_b16 v[148:149], v122 offset:13312
	ds_read_b64_tr_b16 v[204:205], v122 offset:12352
	ds_read_b64_tr_b16 v[206:207], v122 offset:13376
	ds_read_b64_tr_b16 v[208:209], v122 offset:14336
	ds_read_b64_tr_b16 v[210:211], v122 offset:15360
	ds_read_b64_tr_b16 v[212:213], v122 offset:14400
	ds_read_b64_tr_b16 v[214:215], v122 offset:15424
	s_waitcnt lgkmcnt(11)
	v_mfma_f32_32x32x16_bf16 v[64:79], v[126:129], v[80:83], 0
	v_mfma_f32_32x32x16_bf16 v[158:173], v[126:129], v[96:99], 0
	s_waitcnt lgkmcnt(10)
	v_mfma_f32_32x32x16_bf16 v[64:79], v[130:133], v[84:87], v[64:79]
	v_mfma_f32_32x32x16_bf16 v[158:173], v[130:133], v[100:103], v[158:173]
	s_waitcnt lgkmcnt(9)
	v_mfma_f32_32x32x16_bf16 v[64:79], v[138:141], v[88:91], v[64:79]
	v_mfma_f32_32x32x16_bf16 v[158:173], v[138:141], v[104:107], v[158:173]
	s_waitcnt lgkmcnt(8)
	v_mfma_f32_32x32x16_bf16 v[64:79], v[142:145], v[92:95], v[64:79]
	v_mfma_f32_32x32x16_bf16 v[158:173], v[142:145], v[108:111], v[158:173]
	s_nop 10
	v_max3_f32 v152, v64, v65, v66
	v_max3_f32 v150, v158, v159, v160
	v_max3_f32 v152, v152, v67, v68
	v_max3_f32 v150, v150, v161, v162
	v_max3_f32 v152, v152, v69, v70
	v_max3_f32 v150, v150, v163, v164
	v_max3_f32 v152, v152, v71, v72
	v_max3_f32 v150, v150, v165, v166
	v_max3_f32 v152, v152, v73, v74
	v_max3_f32 v150, v150, v167, v168
	v_max3_f32 v152, v152, v75, v76
	v_max3_f32 v150, v150, v169, v170
	v_max3_f32 v152, v152, v77, v78
	v_max3_f32 v150, v150, v171, v172
	v_max_f32_e32 v152, v152, v79
	v_max_f32_e32 v150, v150, v173
	v_mov_b32_e32 v153, v152
	v_mov_b32_e32 v151, v150
	s_nop 1
	s_nop 1
	v_permlane32_swap_b32_e32 v153, v152
	v_permlane32_swap_b32_e32 v151, v150
	v_max_f32_e32 v152, v152, v153
	v_max_f32_e32 v150, v150, v151
	v_sub_f32_e32 v153, v152, v235
	v_sub_f32_e32 v151, v150, v136
	v_cmp_lt_f32_e64 s[10:11], s9, v153
	v_cmp_lt_f32_e64 s[4:5], s9, v151
	s_nop 0
	s_nop 0
	v_cndmask_b32_e64 v202, v235, v152, s[10:11]
	v_cndmask_b32_e64 v200, v136, v150, s[4:5]
	v_sub_f32_e32 v154, v235, v202
	v_sub_f32_e32 v174, v136, v200
	v_exp_f32_e32 v154, v154
	v_exp_f32_e32 v174, v174
	v_sub_f32_e32 v64, v64, v202
	v_sub_f32_e32 v158, v158, v200
	v_sub_f32_e32 v65, v65, v202
	v_sub_f32_e32 v159, v159, v200
	v_sub_f32_e32 v66, v66, v202
	v_sub_f32_e32 v160, v160, v200
	v_sub_f32_e32 v67, v67, v202
	v_sub_f32_e32 v161, v161, v200
	v_sub_f32_e32 v68, v68, v202
	v_sub_f32_e32 v162, v162, v200
	v_sub_f32_e32 v69, v69, v202
	v_sub_f32_e32 v163, v163, v200
	v_sub_f32_e32 v70, v70, v202
	v_sub_f32_e32 v164, v164, v200
	v_sub_f32_e32 v71, v71, v202
	v_sub_f32_e32 v165, v165, v200
	v_sub_f32_e32 v72, v72, v202
	v_sub_f32_e32 v166, v166, v200
	v_sub_f32_e32 v73, v73, v202
	v_sub_f32_e32 v167, v167, v200
	v_sub_f32_e32 v74, v74, v202
	v_sub_f32_e32 v168, v168, v200
	v_sub_f32_e32 v75, v75, v202
	v_sub_f32_e32 v169, v169, v200
	v_sub_f32_e32 v76, v76, v202
	v_sub_f32_e32 v170, v170, v200
	v_sub_f32_e32 v77, v77, v202
	v_sub_f32_e32 v171, v171, v200
	v_sub_f32_e32 v78, v78, v202
	v_sub_f32_e32 v172, v172, v200
	v_sub_f32_e32 v79, v79, v202
	v_sub_f32_e32 v173, v173, v200
	v_mov_b32_e32 v235, v202
	v_mov_b32_e32 v136, v200
	v_exp_f32_e32 v64, v64
	v_exp_f32_e32 v158, v158
	v_exp_f32_e32 v65, v65
	v_exp_f32_e32 v159, v159
	v_exp_f32_e32 v66, v66
	v_exp_f32_e32 v160, v160
	v_add_f32_e32 v182, v64, v65
	v_add_f32_e32 v190, v158, v159
	v_exp_f32_e32 v67, v67
	v_exp_f32_e32 v161, v161
	v_add_f32_e32 v183, v66, v67
	v_add_f32_e32 v191, v160, v161
	v_exp_f32_e32 v68, v68
	v_exp_f32_e32 v162, v162
	v_exp_f32_e32 v69, v69
	v_exp_f32_e32 v163, v163
	v_add_f32_e32 v183, v183, v68
	v_add_f32_e32 v191, v191, v162
	v_exp_f32_e32 v70, v70
	v_exp_f32_e32 v164, v164
	v_add_f32_e32 v182, v182, v69
	v_add_f32_e32 v190, v190, v163
	v_exp_f32_e32 v71, v71
	v_exp_f32_e32 v165, v165
	v_add_f32_e32 v183, v183, v70
	v_add_f32_e32 v191, v191, v164
	v_exp_f32_e32 v72, v72
	v_exp_f32_e32 v166, v166
	v_add_f32_e32 v182, v182, v71
	v_add_f32_e32 v190, v190, v165
	v_exp_f32_e32 v73, v73
	v_exp_f32_e32 v167, v167
	v_add_f32_e32 v183, v183, v72
	v_add_f32_e32 v191, v191, v166
	v_exp_f32_e32 v74, v74
	v_exp_f32_e32 v168, v168
	v_add_f32_e32 v182, v182, v73
	v_add_f32_e32 v190, v190, v167
	v_exp_f32_e32 v75, v75
	v_exp_f32_e32 v169, v169
	v_add_f32_e32 v183, v183, v74
	v_add_f32_e32 v191, v191, v168
	v_exp_f32_e32 v76, v76
	v_exp_f32_e32 v170, v170
	v_add_f32_e32 v182, v182, v75
	v_add_f32_e32 v190, v190, v169
	v_exp_f32_e32 v77, v77
	v_exp_f32_e32 v171, v171
	v_add_f32_e32 v183, v183, v76
	v_add_f32_e32 v191, v191, v170
	v_exp_f32_e32 v78, v78
	v_exp_f32_e32 v172, v172
	v_add_f32_e32 v182, v182, v77
	v_add_f32_e32 v190, v190, v171
	v_exp_f32_e32 v79, v79
	v_exp_f32_e32 v173, v173
	v_add_f32_e32 v183, v183, v78
	v_add_f32_e32 v191, v191, v172
	s_nop 0
	s_nop 0
	v_add_f32_e32 v183, v183, v79
	v_add_f32_e32 v191, v191, v173
	v_add_f32_e32 v182, v182, v183
	v_add_f32_e32 v190, v190, v191
	v_fma_f32 v179, v179, v154, v182
	v_fma_f32 v178, v178, v174, v190
	v_cmp_neq_f32_e32 vcc, 1.0, v154
	s_cbranch_vccz .LaC_nr10
; template <bool KLDS>
; __device__ __forceinline__ void attn_step(const bf16x8 (&kf)[4], LAS const unsigned char* kb, const bf16x8 (&vf)[2][2], const bf16x8 (&qf)[4], f32x16& o0, f32x16& o1, float& m, float& l, int lane, int maskmode) {
;     ...
;     for (int i = 0; i < 16; ++i) { o0[i] *= al; o1[i] *= al; }
	v_pk_mul_f32 v[48:49], v[48:49], v[154:155] op_sel_hi:[1,0]
	v_pk_mul_f32 v[50:51], v[50:51], v[154:155] op_sel_hi:[1,0]
	v_pk_mul_f32 v[52:53], v[52:53], v[154:155] op_sel_hi:[1,0]
	v_pk_mul_f32 v[54:55], v[54:55], v[154:155] op_sel_hi:[1,0]
	v_pk_mul_f32 v[56:57], v[56:57], v[154:155] op_sel_hi:[1,0]
	v_pk_mul_f32 v[58:59], v[58:59], v[154:155] op_sel_hi:[1,0]
	v_pk_mul_f32 v[60:61], v[60:61], v[154:155] op_sel_hi:[1,0]
	v_pk_mul_f32 v[62:63], v[62:63], v[154:155] op_sel_hi:[1,0]
	v_pk_mul_f32 v[32:33], v[32:33], v[154:155] op_sel_hi:[1,0]
	v_pk_mul_f32 v[34:35], v[34:35], v[154:155] op_sel_hi:[1,0]
	v_pk_mul_f32 v[36:37], v[36:37], v[154:155] op_sel_hi:[1,0]
	v_pk_mul_f32 v[38:39], v[38:39], v[154:155] op_sel_hi:[1,0]
	v_pk_mul_f32 v[40:41], v[40:41], v[154:155] op_sel_hi:[1,0]
	v_pk_mul_f32 v[42:43], v[42:43], v[154:155] op_sel_hi:[1,0]
	v_pk_mul_f32 v[44:45], v[44:45], v[154:155] op_sel_hi:[1,0]
	v_pk_mul_f32 v[46:47], v[46:47], v[154:155] op_sel_hi:[1,0]
